# adds P3 second-epilogue gate/Mix loads widened 8B->16B (64->32 loads) in a permutation of their own destination registers (consistent renaming over each round), on top of v45
# speedup vs baseline: 1.0549x; 1.0056x over previous
.LBB0_294:
	s_or_b64 exec, exec, s[6:7]
	s_waitcnt vmcnt(0)
	s_barrier
	v_mbcnt_lo_u32_b32 v242, -1, 0
	v_mbcnt_hi_u32_b32 v242, -1, v242
	v_bfe_u32 v242, v242, 4, 1
	v_mul_u32_u24_e32 v242, 24, v242
	v_mov_b32_e32 v243, 0
	s_nop 0
	v_ashrrev_i32_e32 v133, 31, v132
	v_lshlrev_b64 v[136:137], 12, v[132:133]
	v_ashrrev_i32_e32 v135, 31, v134
	v_lshlrev_b64 v[132:133], 11, v[132:133]
	v_lshl_add_u64 v[136:137], s[76:77], 0, v[136:137]
	v_lshlrev_b64 v[138:139], 1, v[134:135]
	v_lshl_add_u64 v[132:133], s[82:83], 0, v[132:133]
	v_lshl_add_u64 v[134:135], v[136:137], 0, v[138:139]
	v_lshl_add_u64 v[132:133], v[132:133], 0, v[138:139]
	v_lshl_add_u64 v[240:241], v[132:133], 0, v[242:243]
	global_load_dwordx4 v[140:143], v[240:241], off
	global_load_dwordx4 v[144:147], v[240:241], off offset:64
	v_lshl_add_u64 v[240:241], v[134:135], 0, v[242:243]
	global_load_dwordx4 v[148:151], v[240:241], off offset:2048
	global_load_dwordx4 v[152:155], v[240:241], off offset:2112
	v_lshl_add_u64 v[240:241], v[134:135], 0, v[242:243]
	global_load_dwordx4 v[156:159], v[240:241], off offset:2304
	global_load_dwordx4 v[170:173], v[240:241], off offset:2368
	v_lshl_add_u64 v[240:241], v[132:133], 0, v[242:243]
	global_load_dwordx4 v[174:177], v[240:241], off offset:256
	global_load_dwordx4 v[178:181], v[240:241], off offset:320
	v_add_co_u32_e64 v138, s[6:7], s11, v134
	s_waitcnt vmcnt(7)
	v_permlane16_swap_b32_e32 v140, v142
	v_permlane16_swap_b32_e32 v141, v143
	v_lshlrev_b32_e32 v130, 16, v140
	v_addc_co_u32_e64 v139, s[6:7], 0, v135, s[6:7]
	v_add_co_u32_e64 v136, s[6:7], s61, v132
	s_waitcnt vmcnt(5)
	v_permlane16_swap_b32_e32 v148, v150
	v_permlane16_swap_b32_e32 v149, v151
	v_lshlrev_b32_e32 v212, 16, v148
	v_addc_co_u32_e64 v137, s[6:7], 0, v133, s[6:7]
	v_lshl_add_u64 v[240:241], v[138:139], 0, v[242:243]
	global_load_dwordx4 v[182:185], v[240:241], off offset:2048
	global_load_dwordx4 v[186:189], v[240:241], off offset:2112
	v_lshl_add_u64 v[240:241], v[136:137], 0, v[242:243]
	global_load_dwordx4 v[190:193], v[240:241], off
	global_load_dwordx4 v[194:197], v[240:241], off offset:64
	v_lshl_add_u64 v[240:241], v[138:139], 0, v[242:243]
	global_load_dwordx4 v[198:201], v[240:241], off offset:2304
	global_load_dwordx4 v[202:205], v[240:241], off offset:2368
	s_nop 0
	s_nop 0
	v_lshl_add_u64 v[240:241], v[136:137], 0, v[242:243]
	global_load_dwordx4 v[206:209], v[240:241], off offset:256
	global_load_dwordx4 v[244:247], v[240:241], off offset:320
	v_and_b32_e32 v140, 0xffff0000, v140
	v_and_b32_e32 v148, 0xffff0000, v148
	v_lshlrev_b32_e32 v213, 16, v141
	v_lshlrev_b32_e32 v214, 16, v149
	v_and_b32_e32 v141, 0xffff0000, v141
	v_and_b32_e32 v149, 0xffff0000, v149
	s_waitcnt vmcnt(15)
	v_lshlrev_b32_e32 v215, 16, v142
	s_waitcnt vmcnt(13)
	v_lshlrev_b32_e32 v216, 16, v150
	v_and_b32_e32 v142, 0xffff0000, v142
	v_and_b32_e32 v150, 0xffff0000, v150
	v_lshlrev_b32_e32 v217, 16, v143
	v_lshlrev_b32_e32 v218, 16, v151
	v_and_b32_e32 v143, 0xffff0000, v143
	v_and_b32_e32 v151, 0xffff0000, v151
	s_waitcnt vmcnt(14)
	v_permlane16_swap_b32_e32 v144, v146
	v_permlane16_swap_b32_e32 v145, v147
	v_lshlrev_b32_e32 v219, 16, v144
	s_waitcnt vmcnt(12)
	v_permlane16_swap_b32_e32 v152, v154
	v_permlane16_swap_b32_e32 v153, v155
	v_lshlrev_b32_e32 v220, 16, v152
	v_and_b32_e32 v144, 0xffff0000, v144
	v_and_b32_e32 v152, 0xffff0000, v152
	v_lshlrev_b32_e32 v221, 16, v145
	v_lshlrev_b32_e32 v222, 16, v153
	v_and_b32_e32 v145, 0xffff0000, v145
	v_and_b32_e32 v153, 0xffff0000, v153
	v_fmac_f32_e32 v130, v122, v212
	v_fmac_f32_e32 v140, v123, v148
	v_fmac_f32_e32 v213, v124, v214
	v_fmac_f32_e32 v141, v125, v149
	v_fmac_f32_e32 v215, v126, v216
	v_fmac_f32_e32 v142, v127, v150
	v_fmac_f32_e32 v217, v128, v218
	v_fmac_f32_e32 v143, v129, v151
	v_fmac_f32_e32 v219, v118, v220
	v_fmac_f32_e32 v144, v119, v152
	v_fmac_f32_e32 v221, v120, v222
	v_fmac_f32_e32 v145, v121, v153
	v_cvt_pk_bf16_f32 v224, v130, v140
	v_cvt_pk_bf16_f32 v225, v213, v141
	v_cvt_pk_bf16_f32 v226, v215, v142
	v_cvt_pk_bf16_f32 v227, v217, v143
	v_cvt_pk_bf16_f32 v228, v219, v144
	v_cvt_pk_bf16_f32 v229, v221, v145
	s_waitcnt vmcnt(14)
	v_lshlrev_b32_e32 v118, 16, v146
	s_waitcnt vmcnt(12)
	v_lshlrev_b32_e32 v119, 16, v154
	v_fmac_f32_e32 v118, v106, v119
	v_and_b32_e32 v106, 0xffff0000, v146
	v_and_b32_e32 v119, 0xffff0000, v154
	v_fmac_f32_e32 v106, v107, v119
	v_lshlrev_b32_e32 v107, 16, v147
	v_lshlrev_b32_e32 v119, 16, v155
	v_fmac_f32_e32 v107, v108, v119
	v_and_b32_e32 v108, 0xffff0000, v147
	v_and_b32_e32 v119, 0xffff0000, v155
	v_fmac_f32_e32 v108, v109, v119
	v_cvt_pk_bf16_f32 v230, v118, v106
	v_cvt_pk_bf16_f32 v231, v107, v108
	s_nop 1
	v_permlane16_swap_b32_e32 v224, v226
	v_permlane16_swap_b32_e32 v225, v227
	v_permlane16_swap_b32_e32 v228, v230
	v_permlane16_swap_b32_e32 v229, v231
	v_lshl_add_u64 v[240:241], v[132:133], 0, v[242:243]
	global_store_dwordx4 v[240:241], v[224:227], off sc1
	global_store_dwordx4 v[240:241], v[228:231], off offset:64 sc1
	s_waitcnt vmcnt(11)
	v_permlane16_swap_b32_e32 v156, v158
	v_permlane16_swap_b32_e32 v157, v159
	v_permlane16_swap_b32_e32 v174, v176
	v_permlane16_swap_b32_e32 v175, v177
	v_lshlrev_b32_e32 v106, 16, v174
	v_lshlrev_b32_e32 v107, 16, v156
	v_fmac_f32_e32 v106, v114, v107
	v_and_b32_e32 v107, 0xffff0000, v174
	v_and_b32_e32 v108, 0xffff0000, v156
	v_fmac_f32_e32 v107, v115, v108
	v_lshlrev_b32_e32 v108, 16, v175
	v_lshlrev_b32_e32 v109, 16, v157
	v_fmac_f32_e32 v108, v116, v109
	v_and_b32_e32 v109, 0xffff0000, v175
	v_and_b32_e32 v114, 0xffff0000, v157
	v_fmac_f32_e32 v109, v117, v114
	v_cvt_pk_bf16_f32 v232, v106, v107
	v_cvt_pk_bf16_f32 v233, v108, v109
	s_waitcnt vmcnt(11)
	v_lshlrev_b32_e32 v106, 16, v176
	v_lshlrev_b32_e32 v107, 16, v158
	v_fmac_f32_e32 v106, v110, v107
	v_and_b32_e32 v107, 0xffff0000, v176
	v_and_b32_e32 v108, 0xffff0000, v158
	v_fmac_f32_e32 v107, v111, v108
	v_lshlrev_b32_e32 v108, 16, v177
	v_lshlrev_b32_e32 v109, 16, v159
	v_fmac_f32_e32 v108, v112, v109
	v_and_b32_e32 v109, 0xffff0000, v177
	v_and_b32_e32 v110, 0xffff0000, v159
	v_fmac_f32_e32 v109, v113, v110
	v_cvt_pk_bf16_f32 v234, v106, v107
	v_cvt_pk_bf16_f32 v235, v108, v109
	s_waitcnt vmcnt(10)
	v_permlane16_swap_b32_e32 v170, v172
	v_permlane16_swap_b32_e32 v171, v173
	v_permlane16_swap_b32_e32 v178, v180
	v_permlane16_swap_b32_e32 v179, v181
	v_lshlrev_b32_e32 v106, 16, v178
	v_lshlrev_b32_e32 v107, 16, v170
	v_fmac_f32_e32 v106, v102, v107
	v_and_b32_e32 v102, 0xffff0000, v178
	v_and_b32_e32 v107, 0xffff0000, v170
	v_fmac_f32_e32 v102, v103, v107
	v_lshlrev_b32_e32 v103, 16, v179
	v_lshlrev_b32_e32 v107, 16, v171
	v_fmac_f32_e32 v103, v104, v107
	v_and_b32_e32 v104, 0xffff0000, v179
	v_and_b32_e32 v107, 0xffff0000, v171
	v_fmac_f32_e32 v104, v105, v107
	v_cvt_pk_bf16_f32 v236, v106, v102
	v_cvt_pk_bf16_f32 v237, v103, v104
	s_waitcnt vmcnt(10)
	v_lshlrev_b32_e32 v102, 16, v180
	v_lshlrev_b32_e32 v103, 16, v172
	v_fmac_f32_e32 v102, v98, v103
	v_and_b32_e32 v98, 0xffff0000, v180
	v_and_b32_e32 v103, 0xffff0000, v172
	v_fmac_f32_e32 v98, v99, v103
	v_lshlrev_b32_e32 v99, 16, v181
	v_lshlrev_b32_e32 v103, 16, v173
	v_fmac_f32_e32 v99, v100, v103
	v_and_b32_e32 v100, 0xffff0000, v181
	v_and_b32_e32 v103, 0xffff0000, v173
	v_fmac_f32_e32 v100, v101, v103
	v_cvt_pk_bf16_f32 v238, v102, v98
	v_cvt_pk_bf16_f32 v239, v99, v100
	s_nop 1
	v_permlane16_swap_b32_e32 v232, v234
	v_permlane16_swap_b32_e32 v233, v235
	v_permlane16_swap_b32_e32 v236, v238
	v_permlane16_swap_b32_e32 v237, v239
	v_lshl_add_u64 v[240:241], v[132:133], 0, v[242:243]
	global_store_dwordx4 v[240:241], v[232:235], off offset:256 sc1
	global_store_dwordx4 v[240:241], v[236:239], off offset:320 sc1
	s_waitcnt vmcnt(9)
	v_permlane16_swap_b32_e32 v182, v184
	v_permlane16_swap_b32_e32 v183, v185
	v_permlane16_swap_b32_e32 v190, v192
	v_permlane16_swap_b32_e32 v191, v193
	v_lshlrev_b32_e32 v98, 16, v190
	v_lshlrev_b32_e32 v99, 16, v182
	v_fmac_f32_e32 v98, v94, v99
	v_and_b32_e32 v94, 0xffff0000, v190
	v_and_b32_e32 v99, 0xffff0000, v182
	v_fmac_f32_e32 v94, v95, v99
	v_lshlrev_b32_e32 v95, 16, v191
	v_lshlrev_b32_e32 v99, 16, v183
	v_fmac_f32_e32 v95, v96, v99
	v_and_b32_e32 v96, 0xffff0000, v191
	v_and_b32_e32 v99, 0xffff0000, v183
	v_fmac_f32_e32 v96, v97, v99
	v_cvt_pk_bf16_f32 v224, v98, v94
	v_cvt_pk_bf16_f32 v225, v95, v96
	s_waitcnt vmcnt(9)
	v_lshlrev_b32_e32 v94, 16, v192
	v_lshlrev_b32_e32 v95, 16, v184
	v_fmac_f32_e32 v94, v90, v95
	v_and_b32_e32 v90, 0xffff0000, v192
	v_and_b32_e32 v95, 0xffff0000, v184
	v_fmac_f32_e32 v90, v91, v95
	v_lshlrev_b32_e32 v91, 16, v193
	v_lshlrev_b32_e32 v95, 16, v185
	v_fmac_f32_e32 v91, v92, v95
	v_and_b32_e32 v92, 0xffff0000, v193
	v_and_b32_e32 v95, 0xffff0000, v185
	v_fmac_f32_e32 v92, v93, v95
	v_cvt_pk_bf16_f32 v226, v94, v90
	v_cvt_pk_bf16_f32 v227, v91, v92
	s_waitcnt vmcnt(8)
	v_permlane16_swap_b32_e32 v186, v188
	v_permlane16_swap_b32_e32 v187, v189
	v_permlane16_swap_b32_e32 v194, v196
	v_permlane16_swap_b32_e32 v195, v197
	v_lshlrev_b32_e32 v90, 16, v194
	v_lshlrev_b32_e32 v91, 16, v186
	v_fmac_f32_e32 v90, v82, v91
	v_and_b32_e32 v82, 0xffff0000, v194
	v_and_b32_e32 v91, 0xffff0000, v186
	v_fmac_f32_e32 v82, v83, v91
	v_lshlrev_b32_e32 v83, 16, v195
	v_lshlrev_b32_e32 v91, 16, v187
	v_fmac_f32_e32 v83, v84, v91
	v_and_b32_e32 v84, 0xffff0000, v195
	v_and_b32_e32 v91, 0xffff0000, v187
	v_fmac_f32_e32 v84, v85, v91
	v_cvt_pk_bf16_f32 v228, v90, v82
	v_cvt_pk_bf16_f32 v229, v83, v84
	s_waitcnt vmcnt(8)
	v_lshlrev_b32_e32 v82, 16, v196
	v_lshlrev_b32_e32 v83, 16, v188
	v_fmac_f32_e32 v82, v74, v83
	v_and_b32_e32 v74, 0xffff0000, v196
	v_and_b32_e32 v83, 0xffff0000, v188
	v_fmac_f32_e32 v74, v75, v83
	v_lshlrev_b32_e32 v75, 16, v197
	v_lshlrev_b32_e32 v83, 16, v189
	v_fmac_f32_e32 v75, v76, v83
	v_and_b32_e32 v76, 0xffff0000, v197
	v_and_b32_e32 v83, 0xffff0000, v189
	v_fmac_f32_e32 v76, v77, v83
	v_cvt_pk_bf16_f32 v230, v82, v74
	v_cvt_pk_bf16_f32 v231, v75, v76
	s_nop 1
	v_permlane16_swap_b32_e32 v224, v226
	v_permlane16_swap_b32_e32 v225, v227
	v_permlane16_swap_b32_e32 v228, v230
	v_permlane16_swap_b32_e32 v229, v231
	v_lshl_add_u64 v[240:241], v[136:137], 0, v[242:243]
	global_store_dwordx4 v[240:241], v[224:227], off sc1
	global_store_dwordx4 v[240:241], v[228:231], off offset:64 sc1
	s_waitcnt vmcnt(7)
	v_permlane16_swap_b32_e32 v198, v200
	v_permlane16_swap_b32_e32 v199, v201
	v_permlane16_swap_b32_e32 v206, v208
	v_permlane16_swap_b32_e32 v207, v209
	v_lshlrev_b32_e32 v74, 16, v206
	v_lshlrev_b32_e32 v75, 16, v198
	v_fmac_f32_e32 v74, v86, v75
	v_and_b32_e32 v75, 0xffff0000, v206
	v_and_b32_e32 v76, 0xffff0000, v198
	v_fmac_f32_e32 v75, v87, v76
	v_lshlrev_b32_e32 v76, 16, v207
	v_lshlrev_b32_e32 v77, 16, v199
	v_fmac_f32_e32 v76, v88, v77
	v_and_b32_e32 v77, 0xffff0000, v207
	v_and_b32_e32 v82, 0xffff0000, v199
	v_fmac_f32_e32 v77, v89, v82
	v_cvt_pk_bf16_f32 v232, v74, v75
	v_cvt_pk_bf16_f32 v233, v76, v77
	s_waitcnt vmcnt(7)
	v_lshlrev_b32_e32 v74, 16, v208
	v_lshlrev_b32_e32 v75, 16, v200
	v_fmac_f32_e32 v74, v78, v75
	v_and_b32_e32 v75, 0xffff0000, v208
	v_and_b32_e32 v76, 0xffff0000, v200
	v_fmac_f32_e32 v75, v79, v76
	v_lshlrev_b32_e32 v76, 16, v209
	v_lshlrev_b32_e32 v77, 16, v201
	v_fmac_f32_e32 v76, v80, v77
	v_and_b32_e32 v77, 0xffff0000, v209
	v_and_b32_e32 v78, 0xffff0000, v201
	v_fmac_f32_e32 v77, v81, v78
	v_cvt_pk_bf16_f32 v234, v74, v75
	v_cvt_pk_bf16_f32 v235, v76, v77
	s_waitcnt vmcnt(6)
	v_permlane16_swap_b32_e32 v202, v204
	v_permlane16_swap_b32_e32 v203, v205
	v_permlane16_swap_b32_e32 v244, v246
	v_permlane16_swap_b32_e32 v245, v247
	v_lshlrev_b32_e32 v74, 16, v244
	v_lshlrev_b32_e32 v75, 16, v202
	v_fmac_f32_e32 v74, v70, v75
	v_and_b32_e32 v70, 0xffff0000, v244
	v_and_b32_e32 v75, 0xffff0000, v202
	v_fmac_f32_e32 v70, v71, v75
	v_lshlrev_b32_e32 v71, 16, v245
	v_lshlrev_b32_e32 v75, 16, v203
	v_fmac_f32_e32 v71, v72, v75
	v_and_b32_e32 v72, 0xffff0000, v245
	v_and_b32_e32 v75, 0xffff0000, v203
	v_fmac_f32_e32 v72, v73, v75
	v_cvt_pk_bf16_f32 v236, v74, v70
	v_cvt_pk_bf16_f32 v237, v71, v72
	s_waitcnt vmcnt(6)
	v_lshlrev_b32_e32 v70, 16, v246
	v_lshlrev_b32_e32 v71, 16, v204
	v_fmac_f32_e32 v70, v66, v71
	v_and_b32_e32 v66, 0xffff0000, v246
	v_and_b32_e32 v71, 0xffff0000, v204
	v_fmac_f32_e32 v66, v67, v71
	v_lshlrev_b32_e32 v67, 16, v247
	v_lshlrev_b32_e32 v71, 16, v205
	v_fmac_f32_e32 v67, v68, v71
	v_and_b32_e32 v68, 0xffff0000, v247
	v_and_b32_e32 v71, 0xffff0000, v205
	v_fmac_f32_e32 v68, v69, v71
	v_cvt_pk_bf16_f32 v238, v70, v66
	v_cvt_pk_bf16_f32 v239, v67, v68
	s_nop 1
	v_permlane16_swap_b32_e32 v232, v234
	v_permlane16_swap_b32_e32 v233, v235
	v_permlane16_swap_b32_e32 v236, v238
	v_permlane16_swap_b32_e32 v237, v239
	v_lshl_add_u64 v[240:241], v[136:137], 0, v[242:243]
	global_store_dwordx4 v[240:241], v[232:235], off offset:256 sc1
	global_store_dwordx4 v[240:241], v[236:239], off offset:320 sc1
	v_add_co_u32_e64 v68, s[6:7], s62, v134
	s_nop 1
	v_addc_co_u32_e64 v69, s[6:7], 0, v135, s[6:7]
	v_add_co_u32_e64 v90, s[6:7], s64, v132
	s_nop 1
	v_addc_co_u32_e64 v91, s[6:7], 0, v133, s[6:7]
	v_lshl_add_u64 v[240:241], v[90:91], 0, v[242:243]
	global_load_dwordx4 v[72:75], v[240:241], off
	global_load_dwordx4 v[76:79], v[240:241], off offset:64
	v_lshl_add_u64 v[240:241], v[68:69], 0, v[242:243]
	global_load_dwordx4 v[80:83], v[240:241], off offset:2048
	global_load_dwordx4 v[84:87], v[240:241], off offset:2112
	v_add_co_u32_e64 v70, s[6:7], s63, v134
	s_waitcnt vmcnt(3)
	v_permlane16_swap_b32_e32 v72, v74
	v_permlane16_swap_b32_e32 v73, v75
	v_lshlrev_b32_e32 v130, 16, v72
	v_addc_co_u32_e64 v71, s[6:7], 0, v135, s[6:7]
	v_add_co_u32_e64 v66, s[6:7], s65, v132
	s_waitcnt vmcnt(1)
	v_permlane16_swap_b32_e32 v80, v82
	v_permlane16_swap_b32_e32 v81, v83
	v_lshlrev_b32_e32 v136, 16, v80
	v_addc_co_u32_e64 v67, s[6:7], 0, v133, s[6:7]
	v_lshl_add_u64 v[240:241], v[68:69], 0, v[242:243]
	global_load_dwordx4 v[92:95], v[240:241], off offset:2304
	global_load_dwordx4 v[96:99], v[240:241], off offset:2368
	v_lshl_add_u64 v[240:241], v[90:91], 0, v[242:243]
	global_load_dwordx4 v[100:103], v[240:241], off offset:256
	global_load_dwordx4 v[104:107], v[240:241], off offset:320
	v_lshl_add_u64 v[240:241], v[70:71], 0, v[242:243]
	global_load_dwordx4 v[108:111], v[240:241], off offset:2048
	global_load_dwordx4 v[112:115], v[240:241], off offset:2112
	v_lshl_add_u64 v[240:241], v[66:67], 0, v[242:243]
	global_load_dwordx4 v[116:119], v[240:241], off
	global_load_dwordx4 v[120:123], v[240:241], off offset:64
	v_lshl_add_u64 v[240:241], v[70:71], 0, v[242:243]
	global_load_dwordx4 v[124:127], v[240:241], off offset:2304
	global_load_dwordx4 v[132:135], v[240:241], off offset:2368
	v_lshl_add_u64 v[240:241], v[66:67], 0, v[242:243]
	global_load_dwordx4 v[244:247], v[240:241], off offset:256
	global_load_dwordx4 v[250:253], v[240:241], off offset:320
	s_nop 0
	v_and_b32_e32 v72, 0xffff0000, v72
	v_and_b32_e32 v80, 0xffff0000, v80
	v_lshlrev_b32_e32 v137, 16, v73
	v_lshlrev_b32_e32 v138, 16, v81
	v_and_b32_e32 v73, 0xffff0000, v73
	v_and_b32_e32 v81, 0xffff0000, v81
	s_waitcnt vmcnt(15)
	v_lshlrev_b32_e32 v139, 16, v74
	s_waitcnt vmcnt(13)
	v_lshlrev_b32_e32 v140, 16, v82
	v_and_b32_e32 v74, 0xffff0000, v74
	v_and_b32_e32 v82, 0xffff0000, v82
	v_lshlrev_b32_e32 v141, 16, v75
	v_lshlrev_b32_e32 v142, 16, v83
	v_and_b32_e32 v75, 0xffff0000, v75
	v_and_b32_e32 v83, 0xffff0000, v83
	s_waitcnt vmcnt(14)
	v_permlane16_swap_b32_e32 v76, v78
	v_permlane16_swap_b32_e32 v77, v79
	v_lshlrev_b32_e32 v143, 16, v76
	s_waitcnt vmcnt(12)
	v_permlane16_swap_b32_e32 v84, v86
	v_permlane16_swap_b32_e32 v85, v87
	v_lshlrev_b32_e32 v144, 16, v84
	v_and_b32_e32 v76, 0xffff0000, v76
	v_and_b32_e32 v84, 0xffff0000, v84
	v_fmac_f32_e32 v130, v58, v136
	v_fmac_f32_e32 v72, v59, v80
	v_fmac_f32_e32 v137, v60, v138
	v_fmac_f32_e32 v73, v61, v81
	v_fmac_f32_e32 v139, v62, v140
	v_fmac_f32_e32 v74, v63, v82
	v_fmac_f32_e32 v141, v64, v142
	v_fmac_f32_e32 v75, v65, v83
	v_fmac_f32_e32 v143, v54, v144
	v_fmac_f32_e32 v76, v55, v84
	v_cvt_pk_bf16_f32 v224, v130, v72
	v_cvt_pk_bf16_f32 v225, v137, v73
	v_lshlrev_b32_e32 v145, 16, v77
	v_cvt_pk_bf16_f32 v226, v139, v74
	v_cvt_pk_bf16_f32 v227, v141, v75
	v_lshlrev_b32_e32 v54, 16, v85
	v_fmac_f32_e32 v145, v56, v54
	v_and_b32_e32 v55, 0xffff0000, v77
	v_and_b32_e32 v54, 0xffff0000, v85
	v_fmac_f32_e32 v55, v57, v54
	v_cvt_pk_bf16_f32 v228, v143, v76
	v_cvt_pk_bf16_f32 v229, v145, v55
	s_waitcnt vmcnt(14)
	v_lshlrev_b32_e32 v54, 16, v78
	s_waitcnt vmcnt(12)
	v_lshlrev_b32_e32 v55, 16, v86
	v_fmac_f32_e32 v54, v46, v55
	v_and_b32_e32 v46, 0xffff0000, v78
	v_and_b32_e32 v55, 0xffff0000, v86
	v_fmac_f32_e32 v46, v47, v55
	v_lshlrev_b32_e32 v47, 16, v79
	v_lshlrev_b32_e32 v55, 16, v87
	v_fmac_f32_e32 v47, v48, v55
	v_and_b32_e32 v48, 0xffff0000, v79
	v_and_b32_e32 v55, 0xffff0000, v87
	v_fmac_f32_e32 v48, v49, v55
	v_cvt_pk_bf16_f32 v230, v54, v46
	v_cvt_pk_bf16_f32 v231, v47, v48
	s_nop 1
	v_permlane16_swap_b32_e32 v224, v226
	v_permlane16_swap_b32_e32 v225, v227
	v_permlane16_swap_b32_e32 v228, v230
	v_permlane16_swap_b32_e32 v229, v231
	v_lshl_add_u64 v[240:241], v[90:91], 0, v[242:243]
	global_store_dwordx4 v[240:241], v[224:227], off sc1
	global_store_dwordx4 v[240:241], v[228:231], off offset:64 sc1
	s_waitcnt vmcnt(13)
	v_permlane16_swap_b32_e32 v92, v94
	v_permlane16_swap_b32_e32 v93, v95
	v_lshlrev_b32_e32 v47, 16, v92
	v_and_b32_e32 v48, 0xffff0000, v92
	v_lshlrev_b32_e32 v49, 16, v93
	s_waitcnt vmcnt(11)
	v_permlane16_swap_b32_e32 v100, v102
	v_permlane16_swap_b32_e32 v101, v103
	v_lshlrev_b32_e32 v46, 16, v100
	v_fmac_f32_e32 v46, v50, v47
	v_and_b32_e32 v47, 0xffff0000, v100
	v_fmac_f32_e32 v47, v51, v48
	v_lshlrev_b32_e32 v48, 16, v101
	v_fmac_f32_e32 v48, v52, v49
	v_and_b32_e32 v49, 0xffff0000, v101
	v_and_b32_e32 v50, 0xffff0000, v93
	v_fmac_f32_e32 v49, v53, v50
	v_cvt_pk_bf16_f32 v232, v46, v47
	v_cvt_pk_bf16_f32 v233, v48, v49
	s_waitcnt vmcnt(11)
	v_lshlrev_b32_e32 v46, 16, v102
	v_lshlrev_b32_e32 v47, 16, v94
	v_fmac_f32_e32 v46, v42, v47
	v_and_b32_e32 v42, 0xffff0000, v102
	v_and_b32_e32 v47, 0xffff0000, v94
	v_fmac_f32_e32 v42, v43, v47
	v_lshlrev_b32_e32 v43, 16, v103
	v_lshlrev_b32_e32 v47, 16, v95
	v_fmac_f32_e32 v43, v44, v47
	v_and_b32_e32 v44, 0xffff0000, v103
	v_and_b32_e32 v47, 0xffff0000, v95
	v_fmac_f32_e32 v44, v45, v47
	v_cvt_pk_bf16_f32 v234, v46, v42
	v_cvt_pk_bf16_f32 v235, v43, v44
	s_waitcnt vmcnt(10)
	v_permlane16_swap_b32_e32 v96, v98
	v_permlane16_swap_b32_e32 v97, v99
	v_permlane16_swap_b32_e32 v104, v106
	v_permlane16_swap_b32_e32 v105, v107
	v_lshlrev_b32_e32 v42, 16, v104
	v_lshlrev_b32_e32 v43, 16, v96
	v_fmac_f32_e32 v42, v38, v43
	v_and_b32_e32 v38, 0xffff0000, v104
	v_and_b32_e32 v43, 0xffff0000, v96
	v_fmac_f32_e32 v38, v39, v43
	v_lshlrev_b32_e32 v39, 16, v105
	v_lshlrev_b32_e32 v43, 16, v97
	v_fmac_f32_e32 v39, v40, v43
	v_and_b32_e32 v40, 0xffff0000, v105
	v_and_b32_e32 v43, 0xffff0000, v97
	v_fmac_f32_e32 v40, v41, v43
	v_cvt_pk_bf16_f32 v236, v42, v38
	v_cvt_pk_bf16_f32 v237, v39, v40
	s_waitcnt vmcnt(10)
	v_lshlrev_b32_e32 v38, 16, v106
	v_lshlrev_b32_e32 v39, 16, v98
	v_fmac_f32_e32 v38, v34, v39
	v_and_b32_e32 v34, 0xffff0000, v106
	v_and_b32_e32 v39, 0xffff0000, v98
	v_fmac_f32_e32 v34, v35, v39
	v_lshlrev_b32_e32 v35, 16, v107
	v_lshlrev_b32_e32 v39, 16, v99
	v_fmac_f32_e32 v35, v36, v39
	v_and_b32_e32 v36, 0xffff0000, v107
	v_and_b32_e32 v39, 0xffff0000, v99
	v_fmac_f32_e32 v36, v37, v39
	v_cvt_pk_bf16_f32 v238, v38, v34
	v_cvt_pk_bf16_f32 v239, v35, v36
	s_nop 1
	v_permlane16_swap_b32_e32 v232, v234
	v_permlane16_swap_b32_e32 v233, v235
	v_permlane16_swap_b32_e32 v236, v238
	v_permlane16_swap_b32_e32 v237, v239
	v_lshl_add_u64 v[240:241], v[90:91], 0, v[242:243]
	global_store_dwordx4 v[240:241], v[232:235], off offset:256 sc1
	global_store_dwordx4 v[240:241], v[236:239], off offset:320 sc1
	s_waitcnt vmcnt(9)
	v_permlane16_swap_b32_e32 v108, v110
	v_permlane16_swap_b32_e32 v109, v111
	v_permlane16_swap_b32_e32 v116, v118
	v_permlane16_swap_b32_e32 v117, v119
	v_lshlrev_b32_e32 v34, 16, v116
	v_lshlrev_b32_e32 v35, 16, v108
	v_fmac_f32_e32 v34, v30, v35
	v_and_b32_e32 v30, 0xffff0000, v116
	v_and_b32_e32 v35, 0xffff0000, v108
	v_fmac_f32_e32 v30, v31, v35
	v_lshlrev_b32_e32 v31, 16, v117
	v_lshlrev_b32_e32 v35, 16, v109
	v_fmac_f32_e32 v31, v32, v35
	v_and_b32_e32 v32, 0xffff0000, v117
	v_and_b32_e32 v35, 0xffff0000, v109
	v_fmac_f32_e32 v32, v33, v35
	v_cvt_pk_bf16_f32 v224, v34, v30
	v_cvt_pk_bf16_f32 v225, v31, v32
	s_waitcnt vmcnt(9)
	v_lshlrev_b32_e32 v30, 16, v118
	v_lshlrev_b32_e32 v31, 16, v110
	v_fmac_f32_e32 v30, v26, v31
	v_and_b32_e32 v26, 0xffff0000, v118
	v_and_b32_e32 v31, 0xffff0000, v110
	v_fmac_f32_e32 v26, v27, v31
	v_lshlrev_b32_e32 v27, 16, v119
	v_lshlrev_b32_e32 v31, 16, v111
	v_fmac_f32_e32 v27, v28, v31
	v_and_b32_e32 v28, 0xffff0000, v119
	v_and_b32_e32 v31, 0xffff0000, v111
	v_fmac_f32_e32 v28, v29, v31
	v_cvt_pk_bf16_f32 v226, v30, v26
	v_cvt_pk_bf16_f32 v227, v27, v28
	s_waitcnt vmcnt(8)
	v_permlane16_swap_b32_e32 v112, v114
	v_permlane16_swap_b32_e32 v113, v115
	v_permlane16_swap_b32_e32 v120, v122
	v_permlane16_swap_b32_e32 v121, v123
	v_lshlrev_b32_e32 v26, 16, v120
	v_lshlrev_b32_e32 v27, 16, v112
	v_fmac_f32_e32 v26, v22, v27
	v_and_b32_e32 v22, 0xffff0000, v120
	v_and_b32_e32 v27, 0xffff0000, v112
	v_fmac_f32_e32 v22, v23, v27
	v_lshlrev_b32_e32 v23, 16, v121
	v_lshlrev_b32_e32 v27, 16, v113
	v_fmac_f32_e32 v23, v24, v27
	v_and_b32_e32 v24, 0xffff0000, v121
	v_and_b32_e32 v27, 0xffff0000, v113
	v_fmac_f32_e32 v24, v25, v27
	v_cvt_pk_bf16_f32 v228, v26, v22
	v_cvt_pk_bf16_f32 v229, v23, v24
	s_waitcnt vmcnt(8)
	v_lshlrev_b32_e32 v22, 16, v122
	v_lshlrev_b32_e32 v23, 16, v114
	v_fmac_f32_e32 v22, v14, v23
	v_and_b32_e32 v14, 0xffff0000, v122
	v_and_b32_e32 v23, 0xffff0000, v114
	v_fmac_f32_e32 v14, v15, v23
	v_lshlrev_b32_e32 v15, 16, v123
	v_lshlrev_b32_e32 v23, 16, v115
	v_fmac_f32_e32 v15, v16, v23
	v_and_b32_e32 v16, 0xffff0000, v123
	v_and_b32_e32 v23, 0xffff0000, v115
	v_fmac_f32_e32 v16, v17, v23
	v_cvt_pk_bf16_f32 v230, v22, v14
	v_cvt_pk_bf16_f32 v231, v15, v16
	s_nop 1
	v_permlane16_swap_b32_e32 v224, v226
	v_permlane16_swap_b32_e32 v225, v227
	v_permlane16_swap_b32_e32 v228, v230
	v_permlane16_swap_b32_e32 v229, v231
	v_lshl_add_u64 v[240:241], v[66:67], 0, v[242:243]
	global_store_dwordx4 v[240:241], v[224:227], off sc1
	global_store_dwordx4 v[240:241], v[228:231], off offset:64 sc1
	s_waitcnt vmcnt(7)
	v_permlane16_swap_b32_e32 v124, v126
	v_permlane16_swap_b32_e32 v125, v127
	v_permlane16_swap_b32_e32 v244, v246
	v_permlane16_swap_b32_e32 v245, v247
	v_lshlrev_b32_e32 v14, 16, v244
	v_lshlrev_b32_e32 v15, 16, v124
	v_fmac_f32_e32 v14, v18, v15
	v_and_b32_e32 v15, 0xffff0000, v244
	v_and_b32_e32 v16, 0xffff0000, v124
	v_fmac_f32_e32 v15, v19, v16
	v_lshlrev_b32_e32 v16, 16, v245
	v_lshlrev_b32_e32 v17, 16, v125
	v_fmac_f32_e32 v16, v20, v17
	v_and_b32_e32 v17, 0xffff0000, v245
	v_and_b32_e32 v18, 0xffff0000, v125
	v_fmac_f32_e32 v17, v21, v18
	v_cvt_pk_bf16_f32 v232, v14, v15
	v_cvt_pk_bf16_f32 v233, v16, v17
	s_waitcnt vmcnt(7)
	v_lshlrev_b32_e32 v14, 16, v246
	v_lshlrev_b32_e32 v15, 16, v126
	v_fmac_f32_e32 v14, v10, v15
	v_and_b32_e32 v10, 0xffff0000, v246
	v_and_b32_e32 v15, 0xffff0000, v126
	v_fmac_f32_e32 v10, v11, v15
	v_lshlrev_b32_e32 v11, 16, v247
	v_lshlrev_b32_e32 v15, 16, v127
	v_fmac_f32_e32 v11, v12, v15
	v_and_b32_e32 v12, 0xffff0000, v247
	v_and_b32_e32 v15, 0xffff0000, v127
	v_fmac_f32_e32 v12, v13, v15
	v_cvt_pk_bf16_f32 v234, v14, v10
	v_cvt_pk_bf16_f32 v235, v11, v12
	s_waitcnt vmcnt(6)
	v_permlane16_swap_b32_e32 v132, v134
	v_permlane16_swap_b32_e32 v133, v135
	v_permlane16_swap_b32_e32 v250, v252
	v_permlane16_swap_b32_e32 v251, v253
	v_lshlrev_b32_e32 v10, 16, v250
	v_lshlrev_b32_e32 v11, 16, v132
	v_fmac_f32_e32 v10, v6, v11
	v_and_b32_e32 v6, 0xffff0000, v250
	v_and_b32_e32 v11, 0xffff0000, v132
	v_fmac_f32_e32 v6, v7, v11
	v_lshlrev_b32_e32 v7, 16, v251
	v_lshlrev_b32_e32 v11, 16, v133
	v_fmac_f32_e32 v7, v8, v11
	v_and_b32_e32 v8, 0xffff0000, v251
	v_and_b32_e32 v11, 0xffff0000, v133
	v_fmac_f32_e32 v8, v9, v11
	v_cvt_pk_bf16_f32 v236, v10, v6
	v_cvt_pk_bf16_f32 v237, v7, v8
	s_waitcnt vmcnt(6)
	v_lshlrev_b32_e32 v6, 16, v252
	v_lshlrev_b32_e32 v7, 16, v134
	v_fmac_f32_e32 v6, v2, v7
	v_and_b32_e32 v2, 0xffff0000, v252
	v_and_b32_e32 v7, 0xffff0000, v134
	v_fmac_f32_e32 v2, v3, v7
	v_lshlrev_b32_e32 v3, 16, v253
	v_lshlrev_b32_e32 v7, 16, v135
	v_fmac_f32_e32 v3, v4, v7
	v_and_b32_e32 v4, 0xffff0000, v253
	v_and_b32_e32 v7, 0xffff0000, v135
	v_fmac_f32_e32 v4, v5, v7
	v_cvt_pk_bf16_f32 v238, v6, v2
	v_cvt_pk_bf16_f32 v239, v3, v4
	s_nop 1
	v_permlane16_swap_b32_e32 v232, v234
	v_permlane16_swap_b32_e32 v233, v235
	v_permlane16_swap_b32_e32 v236, v238
	v_permlane16_swap_b32_e32 v237, v239
	v_lshl_add_u64 v[240:241], v[66:67], 0, v[242:243]
	global_store_dwordx4 v[240:241], v[232:235], off offset:256 sc1
	global_store_dwordx4 v[240:241], v[236:239], off offset:320 sc1
	s_waitcnt vmcnt(0) lgkmcnt(0)
	s_barrier
	s_and_saveexec_b64 s[50:51], s[4:5]
	s_cbranch_execz .LBB0_281
	s_mov_b64 s[54:55], exec
	v_mbcnt_lo_u32_b32 v2, s54, 0
	v_mbcnt_hi_u32_b32 v2, s55, v2
	v_cmp_eq_u32_e64 s[6:7], 0, v2
	s_and_b64 s[0:1], exec, s[6:7]
	s_mov_b64 exec, s[0:1]
	s_cbranch_execz .LBB0_281
	s_lshl_b32 s0, s48, 4
	s_ashr_i32 s1, s0, 31
	s_lshl_b64 s[0:1], s[0:1], 2
	s_add_u32 s0, s33, s0
	s_addc_u32 s1, s60, s1
	s_bcnt1_i32_b64 s6, s[54:55]
	v_mov_b32_e32 v2, s6
	global_atomic_add v131, v2, s[0:1]
	s_branch .LBB0_281
